# P1 split 171 filter workgroups (3 pairs) / 85 norm workgroups
# speedup vs baseline: 1.0129x; 1.0129x over previous
; #define LAS __attribute__((address_space(3)))
; __device__ __forceinline__ void filter_phase(LAS unsigned char* L, const Args& a) {
;     ...
;     for (int pair = blockIdx.x; pair < 512; pair += gridDim.x) {
;         const int ca = 2 * pair;
;         {
;             LAS bf16_t* WTt = (LAS bf16_t*)WT;
;             for (int idx = tid; idx < 1024; idx += 512) { const int n = idx >> 6, k = idx & 63;
;                 const float v = (n < 4) ? wout[(size_t)k * 2048 + ((n & 2) ? 1024 : 0) + ca + (n & 1)] : 0.f; WTt[idx] = (bf16_t)(pk2(v, 0.f) & 0xffffu); }
;         }
;         __syncthreads();
;         const float da = fabsf(decay[ca]), db = fabsf(decay[ca + 1]);
;         float sa = 0.f, sb = 0.f;
;         {
;             const int lane = tid & 63, w = tid >> 6, n = lane & 15, q = lane >> 4;
;             const bf16x8 b0 = *(const LAS bf16x8*)((const LAS bf16_t*)WT + n * 64 + 8 * q), b1 = *(const LAS bf16x8*)((const LAS bf16_t*)WT + n * 64 + 32 + 8 * q);
;             const float dsel = (n & 1) ? db : da; float ssum = 0.f;
;             LAS float* zf = (LAS float*)z;
; #pragma unroll 1
;             for (int mg = 0; mg < 4; ++mg) {
;             bf16x8 a0v[16], a1v[16];
; #pragma unroll
;             for (int u = 0; u < 16; ++u) { const bf16_t* hp = HDN + (size_t)(16 * (w + 8 * (mg * 16 + u)) + n) * 64 + 8 * q; a0v[u] = *(const bf16x8*)hp; a1v[u] = *(const bf16x8*)(hp + 32); }
; #pragma unroll
;             for (int u = 0; u < 16; ++u) {
;                 const int mt = w + 8 * (mg * 16 + u); const int m0 = 16 * mt; const bf16x8 a0 = a0v[u], a1 = a1v[u];
;                 f32x4 acc = {0.f, 0.f, 0.f, 0.f};
;                 acc = __builtin_amdgcn_mfma_f32_16x16x32_bf16(a0, b0, acc, 0, 0, 0); acc = __builtin_amdgcn_mfma_f32_16x16x32_bf16(a1, b1, acc, 0, 0, 0);
;                 {
;                     const int ml = lane >> 2, nn = lane & 3, src = nn + 16 * (ml >> 2);
;                     const float v0 = __shfl(acc[0], src), v1 = __shfl(acc[1], src), v2 = __shfl(acc[2], src), v3 = __shfl(acc[3], src);
;                     const int isel = ml & 3; float v = isel == 0 ? v0 : isel == 1 ? v1 : isel == 2 ? v2 : v3;
;                     const int m = m0 + ml; const float t = (float)m / (float)(SEQ - 1); v *= expf(-t * ((nn & 1) ? db : da));
;                     if (nn < 2) { zf[2 * PH(m) + nn] = v; ssum += fabsf(v); }
.LBB0_124:
	s_or_b64 exec, exec, s[8:9]
	s_movk_i32 s23, 0x1ff
	s_mul_i32 s97, s3, 0xab
	s_lshr_b32 s97, s97, 8
	s_cmp_ge_i32 s2, s97
	v_and_b32_e32 v153, 63, v152
	v_lshrrev_b32_e32 v133, 6, v152
	v_mov_b32_e32 v129, 0
	s_waitcnt lgkmcnt(0)
	s_barrier
	s_cbranch_scc1 .LBB0_313
	s_add_u32 s25, s28, 0x3600000
	s_addc_u32 s70, s29, 0
	s_add_u32 s71, s28, 0x80000
	s_addc_u32 s72, s29, 0
	s_add_i32 s73, 0, 0x20400
	v_and_b32_e32 v2, 1, v152
	v_lshl_add_u32 v158, v0, 3, s73
	v_and_b32_e32 v0, 56, v153
	s_add_i32 s24, 0, 0x20000
	v_cmp_eq_u32_e64 s[0:1], 0, v2
	v_add_u32_e32 v160, s24, v0
	v_and_b32_e32 v2, 0xf0, v152
	v_lshlrev_b32_e32 v4, 8, v152
	s_movk_i32 s24, 0xf00
	v_and_or_b32 v11, v4, s24, v2
	v_and_b32_e32 v2, 1, v133
	v_lshlrev_b32_e32 v0, 7, v152
	v_lshlrev_b32_e32 v128, 2, v2
	v_lshrrev_b32_e32 v2, 8, v152
	v_and_b32_e32 v0, 0x380, v0
	v_or_b32_e32 v2, v11, v2
	v_add_u32_e32 v161, s73, v0
	v_lshlrev_b32_e32 v164, 2, v152
	v_lshrrev_b32_e32 v0, 2, v152
	v_sub_u32_e32 v4, 0, v2
	v_and_b32_e32 v165, 60, v0
	v_lshlrev_b32_e32 v6, 10, v4
	v_lshrrev_b32_e32 v10, 6, v4
	v_bitop3_b32 v0, v0, v164, 60 bitop3:0x6c
	v_and_b32_e32 v6, 0x3c00, v6
	v_lshlrev_b32_e32 v8, 2, v4
	v_and_b32_e32 v10, 60, v10
	v_bfe_u32 v12, v4, 12, 2
	v_lshl_add_u32 v167, v0, 3, 0
	v_lshrrev_b32_e32 v0, 2, v4
	v_and_b32_e32 v8, 0x3c0, v8
	v_or3_b32 v6, v12, v10, v6
	v_and_b32_e32 v0, 60, v0
	v_sub_u32_e32 v2, 0x3000, v2
	v_bitop3_b32 v0, v6, v0, v8 bitop3:0x36
	v_lshlrev_b32_e32 v10, 10, v2
	v_lshlrev_b32_e32 v12, 2, v2
	v_lshrrev_b32_e32 v13, 6, v2
	v_lshrrev_b32_e32 v14, 12, v2
	v_lshl_add_u32 v168, v0, 3, 0
	v_lshrrev_b32_e32 v0, 2, v2
	v_add_u32_e32 v2, 0x200, v152
	v_lshrrev_b32_e32 v4, 8, v2
	v_and_b32_e32 v10, 0x3c00, v10
	v_and_b32_e32 v13, 60, v13
	v_or_b32_e32 v4, v11, v4
	v_and_b32_e32 v12, 0x3c0, v12
	v_or3_b32 v10, v13, v14, v10
	v_and_b32_e32 v0, 60, v0
	v_sub_u32_e32 v6, 0, v4
	v_bitop3_b32 v0, v10, v0, v12 bitop3:0x36
	v_lshlrev_b32_e32 v8, 10, v6
	v_lshlrev_b32_e32 v10, 2, v6
	v_lshrrev_b32_e32 v12, 6, v6
	v_and_b32_e32 v8, 0x3c00, v8
	v_and_b32_e32 v10, 0x3c0, v10
	v_and_b32_e32 v12, 60, v12
	v_sub_u32_e32 v4, 0x3000, v4
	v_or3_b32 v8, v12, v8, v10
	v_lshrrev_b32_e32 v10, 6, v4
	v_lshlrev_b32_e32 v12, 2, v4
	v_lshl_or_b32 v10, v4, 10, v10
	v_and_b32_e32 v12, 0x3c0, v12
	s_movk_i32 s24, 0x3c3c
	v_lshrrev_b32_e32 v4, 2, v4
	v_and_or_b32 v10, v10, s24, v12
	v_lshrrev_b32_e32 v6, 2, v6
	v_and_b32_e32 v4, 60, v4
	v_and_b32_e32 v6, 60, v6
	v_bitop3_b32 v4, v10, v4, 2 bitop3:0x36
	v_bitop3_b32 v6, v8, v6, 3 bitop3:0x36
	v_lshl_add_u32 v172, v4, 3, 0
	v_or_b32_e32 v4, 0x400, v152
	v_lshl_add_u32 v171, v6, 3, 0
	v_lshrrev_b32_e32 v6, 8, v4
	v_or_b32_e32 v6, v11, v6
	v_lshlrev_b32_e32 v12, 5, v2
	v_lshlrev_b32_e32 v13, 3, v165
	v_sub_u32_e32 v8, 0, v6
	v_xad_u32 v170, v12, v13, 0
	v_lshlrev_b32_e32 v10, 10, v8
	v_lshlrev_b32_e32 v12, 2, v8
	v_lshrrev_b32_e32 v14, 6, v8
	v_and_b32_e32 v10, 0x3c00, v10
	v_and_b32_e32 v12, 0x3c0, v12
	v_and_b32_e32 v14, 60, v14
	v_sub_u32_e32 v6, 0x3000, v6
	v_or3_b32 v10, v14, v10, v12
	v_lshrrev_b32_e32 v12, 6, v6
	v_lshlrev_b32_e32 v14, 2, v6
	v_lshl_or_b32 v12, v6, 10, v12
	v_and_b32_e32 v14, 0x3c0, v14
	v_lshrrev_b32_e32 v6, 2, v6
	v_and_or_b32 v12, v12, s24, v14
	v_lshrrev_b32_e32 v8, 2, v8
	v_and_b32_e32 v6, 60, v6
	v_and_b32_e32 v8, 60, v8
	v_bitop3_b32 v6, v12, v6, 2 bitop3:0x36
	v_bitop3_b32 v8, v10, v8, 3 bitop3:0x36
	v_lshl_add_u32 v175, v6, 3, 0
	v_add_u32_e32 v6, 0x600, v152
	v_lshl_add_u32 v174, v8, 3, 0
	v_lshrrev_b32_e32 v8, 8, v6
	v_or_b32_e32 v8, v11, v8
	v_lshlrev_b32_e32 v14, 5, v4
	v_sub_u32_e32 v10, 0, v8
	v_xad_u32 v173, v14, v13, 0
	v_lshlrev_b32_e32 v12, 10, v10
	v_lshlrev_b32_e32 v14, 2, v10
	v_lshrrev_b32_e32 v15, 6, v10
	v_and_b32_e32 v12, 0x3c00, v12
	v_and_b32_e32 v14, 0x3c0, v14
	v_and_b32_e32 v15, 60, v15
	v_sub_u32_e32 v8, 0x3000, v8
	v_or3_b32 v12, v15, v12, v14
	v_lshrrev_b32_e32 v14, 6, v8
	v_lshlrev_b32_e32 v15, 2, v8
	v_lshl_or_b32 v14, v8, 10, v14
	v_and_b32_e32 v15, 0x3c0, v15
	v_lshrrev_b32_e32 v8, 2, v8
	v_and_or_b32 v14, v14, s24, v15
	v_lshrrev_b32_e32 v10, 2, v10
	v_and_b32_e32 v8, 60, v8
	v_and_b32_e32 v10, 60, v10
	v_bitop3_b32 v8, v14, v8, 2 bitop3:0x36
	v_bitop3_b32 v10, v12, v10, 3 bitop3:0x36
	v_lshl_add_u32 v178, v8, 3, 0
	v_or_b32_e32 v8, 0x800, v152
	v_lshl_add_u32 v177, v10, 3, 0
	v_lshrrev_b32_e32 v10, 8, v8
	v_or_b32_e32 v10, v11, v10
	v_lshlrev_b32_e32 v15, 5, v6
	v_sub_u32_e32 v12, 0, v10
	v_xad_u32 v176, v15, v13, 0
	v_lshlrev_b32_e32 v14, 10, v12
	v_lshlrev_b32_e32 v15, 2, v12
	v_lshrrev_b32_e32 v16, 6, v12
	v_and_b32_e32 v14, 0x3c00, v14
	v_and_b32_e32 v15, 0x3c0, v15
	v_and_b32_e32 v16, 60, v16
	v_sub_u32_e32 v10, 0x3000, v10
	v_or3_b32 v14, v16, v14, v15
	v_lshrrev_b32_e32 v15, 6, v10
	v_lshlrev_b32_e32 v16, 2, v10
	v_lshl_or_b32 v15, v10, 10, v15
	v_and_b32_e32 v16, 0x3c0, v16
	v_lshrrev_b32_e32 v10, 2, v10
	v_and_or_b32 v15, v15, s24, v16
	v_lshrrev_b32_e32 v12, 2, v12
	v_and_b32_e32 v10, 60, v10
	v_and_b32_e32 v12, 60, v12
	v_bitop3_b32 v10, v15, v10, 2 bitop3:0x36
	v_bitop3_b32 v12, v14, v12, 3 bitop3:0x36
	v_lshl_add_u32 v181, v10, 3, 0
	v_add_u32_e32 v10, 0xa00, v152
	v_lshl_add_u32 v180, v12, 3, 0
	v_lshrrev_b32_e32 v12, 8, v10
	v_or_b32_e32 v12, v11, v12
	v_lshlrev_b32_e32 v16, 5, v8
	v_sub_u32_e32 v14, 0, v12
	v_xad_u32 v179, v16, v13, 0
	v_lshlrev_b32_e32 v15, 10, v14
	v_lshlrev_b32_e32 v16, 2, v14
	v_lshrrev_b32_e32 v17, 6, v14
	v_and_b32_e32 v15, 0x3c00, v15
	v_and_b32_e32 v16, 0x3c0, v16
	v_and_b32_e32 v17, 60, v17
	v_sub_u32_e32 v12, 0x3000, v12
	v_or3_b32 v15, v17, v15, v16
	v_lshrrev_b32_e32 v16, 6, v12
	v_lshlrev_b32_e32 v17, 2, v12
; #define LAS __attribute__((address_space(3)))
; __device__ __forceinline__ void filter_phase(LAS unsigned char* L, const Args& a) {
;     ...
;     for (int pair = blockIdx.x; pair < 512; pair += gridDim.x) {
;         const int ca = 2 * pair;
;         {
;             LAS bf16_t* WTt = (LAS bf16_t*)WT;
;             for (int idx = tid; idx < 1024; idx += 512) { const int n = idx >> 6, k = idx & 63;
;                 const float v = (n < 4) ? wout[(size_t)k * 2048 + ((n & 2) ? 1024 : 0) + ca + (n & 1)] : 0.f; WTt[idx] = (bf16_t)(pk2(v, 0.f) & 0xffffu); }
;         }
;         __syncthreads();
;         const float da = fabsf(decay[ca]), db = fabsf(decay[ca + 1]);
;         float sa = 0.f, sb = 0.f;
;         {
;             const int lane = tid & 63, w = tid >> 6, n = lane & 15, q = lane >> 4;
;             const bf16x8 b0 = *(const LAS bf16x8*)((const LAS bf16_t*)WT + n * 64 + 8 * q), b1 = *(const LAS bf16x8*)((const LAS bf16_t*)WT + n * 64 + 32 + 8 * q);
;             const float dsel = (n & 1) ? db : da; float ssum = 0.f;
;             LAS float* zf = (LAS float*)z;
; #pragma unroll 1
;             for (int mg = 0; mg < 4; ++mg) {
;             bf16x8 a0v[16], a1v[16];
; #pragma unroll
;             for (int u = 0; u < 16; ++u) { const bf16_t* hp = HDN + (size_t)(16 * (w + 8 * (mg * 16 + u)) + n) * 64 + 8 * q; a0v[u] = *(const bf16x8*)hp; a1v[u] = *(const bf16x8*)(hp + 32); }
; #pragma unroll
;             for (int u = 0; u < 16; ++u) {
;                 const int mt = w + 8 * (mg * 16 + u); const int m0 = 16 * mt; const bf16x8 a0 = a0v[u], a1 = a1v[u];
;                 f32x4 acc = {0.f, 0.f, 0.f, 0.f};
;                 acc = __builtin_amdgcn_mfma_f32_16x16x32_bf16(a0, b0, acc, 0, 0, 0); acc = __builtin_amdgcn_mfma_f32_16x16x32_bf16(a1, b1, acc, 0, 0, 0);
;                 {
;                     const int ml = lane >> 2, nn = lane & 3, src = nn + 16 * (ml >> 2);
;                     const float v0 = __shfl(acc[0], src), v1 = __shfl(acc[1], src), v2 = __shfl(acc[2], src), v3 = __shfl(acc[3], src);
;                     const int isel = ml & 3; float v = isel == 0 ? v0 : isel == 1 ? v1 : isel == 2 ? v2 : v3;
;                     const int m = m0 + ml; const float t = (float)m / (float)(SEQ - 1); v *= expf(-t * ((nn & 1) ? db : da));
;                     if (nn < 2) { zf[2 * PH(m) + nn] = v; ssum += fabsf(v); }
	v_lshl_or_b32 v16, v12, 10, v16
	v_and_b32_e32 v17, 0x3c0, v17
	v_lshrrev_b32_e32 v12, 2, v12
	v_and_or_b32 v16, v16, s24, v17
	v_lshrrev_b32_e32 v14, 2, v14
	v_and_b32_e32 v12, 60, v12
	v_and_b32_e32 v14, 60, v14
	v_bitop3_b32 v12, v16, v12, 2 bitop3:0x36
	v_bitop3_b32 v14, v15, v14, 3 bitop3:0x36
	v_lshl_add_u32 v184, v12, 3, 0
	v_or_b32_e32 v12, 0xc00, v152
	v_lshl_add_u32 v183, v14, 3, 0
	v_lshrrev_b32_e32 v14, 8, v12
	v_or_b32_e32 v14, v11, v14
	v_lshlrev_b32_e32 v17, 5, v10
	v_sub_u32_e32 v15, 0, v14
	v_xad_u32 v182, v17, v13, 0
	v_lshlrev_b32_e32 v16, 10, v15
	v_lshlrev_b32_e32 v17, 2, v15
	v_lshrrev_b32_e32 v18, 6, v15
	v_and_b32_e32 v16, 0x1c00, v16
	v_and_b32_e32 v17, 0x3c0, v17
	v_and_b32_e32 v18, 60, v18
	v_sub_u32_e32 v14, 0x3000, v14
	v_or3_b32 v16, v18, v16, v17
	v_lshrrev_b32_e32 v17, 6, v14
	v_lshlrev_b32_e32 v18, 2, v14
	v_lshl_or_b32 v17, v14, 10, v17
	v_and_b32_e32 v18, 0x3c0, v18
	s_movk_i32 s33, 0x1c3c
	v_lshrrev_b32_e32 v14, 2, v14
	v_and_or_b32 v17, v17, s33, v18
	v_lshrrev_b32_e32 v15, 2, v15
	v_and_b32_e32 v14, 60, v14
	v_and_b32_e32 v15, 60, v15
	v_bitop3_b32 v14, v17, v14, 2 bitop3:0x36
	v_bitop3_b32 v15, v16, v15, 3 bitop3:0x36
	v_lshl_add_u32 v187, v14, 3, 0
	v_add_u32_e32 v14, 0xe00, v152
	v_lshl_add_u32 v186, v15, 3, 0
	v_lshrrev_b32_e32 v15, 8, v14
	v_or_b32_e32 v11, v11, v15
	v_lshlrev_b32_e32 v18, 5, v12
	v_sub_u32_e32 v15, 0, v11
	v_xad_u32 v185, v18, v13, 0
	v_lshlrev_b32_e32 v16, 10, v15
	v_lshlrev_b32_e32 v17, 2, v15
	v_lshrrev_b32_e32 v18, 6, v15
	v_and_b32_e32 v16, 0x3c00, v16
	v_and_b32_e32 v17, 0x3c0, v17
	v_and_b32_e32 v18, 60, v18
	v_sub_u32_e32 v11, 0x3000, v11
	v_or3_b32 v16, v18, v16, v17
	v_lshrrev_b32_e32 v17, 6, v11
	v_lshlrev_b32_e32 v18, 2, v11
	v_lshl_or_b32 v17, v11, 10, v17
	v_and_b32_e32 v18, 0x3c0, v18
	v_lshrrev_b32_e32 v11, 2, v11
	v_and_or_b32 v17, v17, s24, v18
	v_lshlrev_b32_e32 v18, 5, v14
	v_and_b32_e32 v11, 60, v11
	v_xad_u32 v188, v18, v13, 0
	v_lshrrev_b32_e32 v13, 2, v15
	v_bitop3_b32 v11, v17, v11, 2 bitop3:0x36
	v_and_b32_e32 v13, 60, v13
	v_lshl_add_u32 v190, v11, 3, 0
	v_mbcnt_lo_u32_b32 v11, -1, 0
	v_bitop3_b32 v13, v16, v13, 3 bitop3:0x36
	v_mbcnt_hi_u32_b32 v11, -1, v11
	v_lshl_add_u32 v189, v13, 3, 0
	v_and_b32_e32 v13, 64, v11
	v_and_or_b32 v15, v152, 51, v13
	v_lshlrev_b32_e32 v191, 2, v15
	v_add_u32_e32 v13, 64, v13
	v_xor_b32_e32 v15, 1, v11
	v_cmp_lt_i32_e32 vcc, v15, v13
	v_lshrrev_b32_e32 v5, 2, v153
	v_and_b32_e32 v1, 15, v152
	v_cndmask_b32_e32 v15, v11, v15, vcc
	v_lshlrev_b32_e32 v192, 2, v15
	v_xor_b32_e32 v15, 2, v11
	v_cmp_lt_i32_e32 vcc, v15, v13
	v_lshl_or_b32 v5, v133, 4, v5
	v_lshlrev_b32_e32 v1, 7, v1
	v_cndmask_b32_e32 v15, v11, v15, vcc
	v_lshlrev_b32_e32 v193, 2, v15
	v_xor_b32_e32 v15, 4, v11
	v_cmp_lt_i32_e32 vcc, v15, v13
	s_add_i32 s22, 0, 0x20800
	v_and_b32_e32 v3, 48, v152
	v_cndmask_b32_e32 v15, v11, v15, vcc
	v_lshlrev_b32_e32 v194, 2, v15
	v_xor_b32_e32 v15, 8, v11
	v_cmp_lt_i32_e32 vcc, v15, v13
	v_lshl_add_u32 v169, v0, 3, 0
	v_lshlrev_b32_e32 v0, 1, v152
	v_cndmask_b32_e32 v15, v11, v15, vcc
	v_lshlrev_b32_e32 v195, 2, v15
	v_xor_b32_e32 v15, 16, v11
	v_cmp_lt_i32_e32 vcc, v15, v13
	v_add_u32_e32 v202, 0x780, v5
	v_sub_u32_e32 v203, 0x3880, v5
	v_cndmask_b32_e32 v15, v11, v15, vcc
	v_lshlrev_b32_e32 v196, 2, v15
	v_xor_b32_e32 v15, 32, v11
	v_cmp_lt_i32_e32 vcc, v15, v13
	v_lshlrev_b32_e32 v5, 5, v152
	v_add3_u32 v154, s22, v1, v3
	v_cndmask_b32_e32 v11, v11, v15, vcc
	v_lshlrev_b32_e32 v197, 2, v11
	v_add_u32_e32 v200, s22, v0
	s_movk_i32 s22, 0x780
	v_and_b32_e32 v5, 0x7800, v5
	v_lshlrev_b32_e32 v11, 5, v153
	v_and_or_b32 v132, v11, s22, v5
	v_lshlrev_b32_e32 v5, 11, v133
	v_lshl_add_u64 v[130:131], s[82:83], 0, v[128:129]
	v_or3_b32 v128, v5, v1, v3
	v_add_u32_e32 v16, 0x4000, v128
	v_mov_b32_e32 v17, v129
	v_lshl_add_u64 v[136:137], s[28:29], 0, v[16:17]
	v_add_u32_e32 v16, 0xc000, v128
	v_lshl_add_u64 v[138:139], s[28:29], 0, v[16:17]
	v_add_u32_e32 v16, 0x14000, v128
	v_lshl_add_u64 v[140:141], s[28:29], 0, v[16:17]
	v_add_u32_e32 v16, 0x1c000, v128
	v_and_b32_e32 v155, 3, v152
	v_lshlrev_b32_e32 v7, 3, v133
	v_lshl_add_u64 v[142:143], s[28:29], 0, v[16:17]
	v_add_u32_e32 v16, 0x24000, v128
	v_lshlrev_b32_e32 v9, 4, v155
	v_lshl_add_u64 v[144:145], s[28:29], 0, v[16:17]
	v_add_u32_e32 v16, 0x2c000, v128
	v_add_u32_e32 v1, 0, v7
	v_bfe_u32 v156, v153, 2, 2
	v_and_b32_e32 v162, 60, v152
	v_lshlrev_b32_e32 v2, 1, v2
	v_lshlrev_b32_e32 v4, 1, v4
	v_lshlrev_b32_e32 v6, 1, v6
	v_lshlrev_b32_e32 v8, 1, v8
	v_lshlrev_b32_e32 v10, 1, v10
	v_lshlrev_b32_e32 v12, 1, v12
	v_lshlrev_b32_e32 v14, 1, v14
	v_lshl_add_u64 v[134:135], s[28:29], 0, v[128:129]
	v_lshl_add_u64 v[146:147], s[28:29], 0, v[16:17]
	v_add_u32_e32 v16, 0x34000, v128
	v_add_u32_e32 v128, 0x3c000, v128
	v_add_u32_e32 v204, 0x21000, v1
	s_mov_b32 s38, 0x3f3504f3
	s_mov_b32 s42, 0xbec3ef15
	v_add_u32_e32 v1, 0, v9
	s_mov_b32 s44, 0.5
	v_cmp_lt_u32_e64 s[10:11], 1, v155
	v_lshl_add_u32 v157, v155, 2, 0
	v_cmp_eq_u32_e64 s[4:5], 2, v156
	v_cmp_eq_u32_e64 s[6:7], 0, v152
	v_cmp_eq_u32_e64 s[8:9], 0, v153
	v_lshlrev_b32_e32 v159, 4, v152
	v_lshl_add_u32 v163, v162, 3, 0
	v_and_b32_e32 v166, 12, v133
	v_lshlrev_b32_e32 v198, 11, v152
	v_lshlrev_b32_e32 v199, 3, v152
	v_add_u32_e32 v201, 0x78, v133
	v_lshl_add_u64 v[148:149], s[28:29], 0, v[16:17]
	v_lshl_add_u64 v[150:151], s[28:29], 0, v[128:129]
	s_movk_i32 s74, 0x100
	s_mov_b32 s75, 0x1f800
	s_mov_b32 s76, 0x300000
	s_mov_b32 s77, 0xc5fff800
	s_mov_b32 s78, 0x3fb8aa3b
	s_mov_b32 s79, 0xc2ce8ed0
	s_mov_b32 s80, 0x42b17218
	s_add_i32 s81, 0, 0x10000
	s_add_i32 s82, 0, 0x21010
	s_add_i32 s83, 0, 0x21020
	s_add_i32 s86, 0, 0x21030
	s_mov_b32 s22, 0x3f6c835e
	s_mov_b32 s24, 0x3ec3ef15
	s_mov_b32 s39, 0xbf3504f3
	s_mov_b32 s43, 0xbf6c835e
	v_add_u32_e32 v205, 0x20000, v1
	s_movk_i32 s87, 0x7fc0
	s_mov_b32 s45, -0.5
	v_lshlrev_b32_e32 v206, 4, v0
	v_lshlrev_b32_e32 v207, 4, v2
	v_lshlrev_b32_e32 v208, 4, v4
	v_lshlrev_b32_e32 v209, 4, v6
	v_lshlrev_b32_e32 v210, 4, v8
	v_lshlrev_b32_e32 v211, 4, v10
	v_lshlrev_b32_e32 v212, 4, v12
	v_lshlrev_b32_e32 v213, 4, v14
	v_mov_b32_e32 v214, 0x7f800000
	v_mov_b32_e32 v224, v129
	v_mov_b32_e32 v225, v129
	s_mov_b32 s46, s2
	s_branch .LBB0_127

; __device__ __forceinline__ void norm_rows(const float* x, int nrows, const float* g, const float* sc, const float* sh, bf16_t* o, int lane) {
;     f32x4 gs[4], shv[4];
; #pragma unroll
;     for (int j = 0; j < 4; ++j) { const int k = 4 * lane + 256 * j; const f32x4 gg = *(const f32x4*)(g + k), s = *(const f32x4*)(sc + k); gs[j] = gg * (1.0f + s); shv[j] = *(const f32x4*)(sh + k); }
;     int r0 = 0;
; #pragma unroll 1
;     for (; r0 + 4 <= nrows; r0 += 4) {
; __device__ __forceinline__ void norm_phase(const Args& a, const float* x, int layer, int which  , bool with_ctx) {
;     const int tid = threadIdx.x, lane = tid & 63, w = tid >> 6; const int gw = blockIdx.x * 8 + w, NGW = gridDim.x * 8;
;     const float* MOD = (const float*)(a.ws + WS_MOD) + (size_t)layer * 9 * 6144;
;     const float* g = (which ? a.in[7] : a.in[6]) + layer * 1024;
;     bf16_t* XN = (bf16_t*)(a.ws + WS_XN);
;     const int c0 = which ? 3 : 0;
;     for (int chunk = gw; chunk < M_ / 32; chunk += NGW) { const int row = chunk * 32, b = row / SEQ; const float* mb = MOD + (size_t)b * 6144;
;         norm_rows(x + (size_t)row * 1024, 32, g, mb + (c0 + 1) * 1024, mb + c0 * 1024, XN + (size_t)row * 1024, lane); }
;     if (with_ctx) { const float* mb = MOD + (size_t)8 * 6144;
;         for (int row = gw; row < MCTX; row += NGW) norm_rows(a.in[2] + (size_t)row * 1024, 1, g, mb + (c0 + 1) * 1024, mb + c0 * 1024, XN + (size_t)(M_ + row) * 1024, lane); }
; }
.LBB0_313:
	s_mul_i32 s97, s3, 0xab
	s_lshr_b32 s97, s97, 8
	s_cmp_lt_i32 s2, s97
	s_cbranch_scc1 .LBB0_321
	s_sub_i32 s95, s2, s97
	s_sub_i32 s94, s3, s97
	v_lshl_add_u32 v32, s95, 3, v133
	s_movk_i32 s0, 0x800
	v_cmp_gt_i32_e32 vcc, s0, v32
	s_and_saveexec_b64 s[8:9], vcc
	s_cbranch_execz .LBB0_320
	v_mbcnt_lo_u32_b32 v1, -1, 0
	v_mbcnt_hi_u32_b32 v1, -1, v1
	v_and_b32_e32 v3, 64, v1
	v_add_u32_e32 v3, 64, v3
	v_xor_b32_e32 v5, 1, v1
	v_cmp_lt_i32_e32 vcc, v5, v3
	v_mov_b32_e32 v37, 0
	v_lshlrev_b32_e32 v38, 3, v153
	v_cndmask_b32_e32 v5, v1, v5, vcc
	v_lshlrev_b32_e32 v80, 2, v5
	v_xor_b32_e32 v5, 2, v1
	v_cmp_lt_i32_e32 vcc, v5, v3
	v_mov_b32_e32 v39, v37
	v_lshlrev_b32_e32 v0, 2, v153
	v_cndmask_b32_e32 v5, v1, v5, vcc
	v_lshlrev_b32_e32 v81, 2, v5
	v_xor_b32_e32 v5, 4, v1
	v_cmp_lt_i32_e32 vcc, v5, v3
	v_lshlrev_b32_e32 v36, 4, v153
	v_lshl_add_u64 v[8:9], s[28:29], 0, v[38:39]
	v_cndmask_b32_e32 v5, v1, v5, vcc
	v_lshlrev_b32_e32 v82, 2, v5
	v_xor_b32_e32 v5, 8, v1
	v_cmp_lt_i32_e32 vcc, v5, v3
	s_mov_b64 s[0:1], 0x7601e00
	v_or_b32_e32 v2, 0x100, v0
	v_cndmask_b32_e32 v5, v1, v5, vcc
	v_lshlrev_b32_e32 v83, 2, v5
	v_xor_b32_e32 v5, 16, v1
	v_cmp_lt_i32_e32 vcc, v5, v3
	v_or_b32_e32 v4, 0x200, v0
	v_or_b32_e32 v6, 0x300, v0
	v_cndmask_b32_e32 v5, v1, v5, vcc
	v_lshlrev_b32_e32 v84, 2, v5
	v_xor_b32_e32 v5, 32, v1
	v_cmp_lt_i32_e32 vcc, v5, v3
	v_lshl_add_u64 v[48:49], v[8:9], 0, s[0:1]
	v_lshl_add_u64 v[8:9], s[36:37], 0, v[36:37]
	v_cndmask_b32_e32 v1, v1, v5, vcc
	v_lshlrev_b32_e32 v85, 2, v1
	v_lshlrev_b32_e32 v1, 5, v133
	s_mov_b64 s[0:1], 0x3c00
	s_lshl_b32 s10, s94, 3
	v_lshl_add_u64 v[34:35], s[48:49], 0, v[36:37]
	v_lshl_add_u32 v50, s95, 8, v1
	s_lshl_b32 s11, s94, 8
	v_lshl_add_u64 v[52:53], v[8:9], 0, s[0:1]
	s_mov_b64 s[12:13], 0
	s_mov_b64 s[22:23], 0x1000
	v_lshlrev_b32_e32 v46, 2, v0
	v_mov_b32_e32 v47, v37
	v_lshlrev_b32_e32 v44, 2, v2
	v_mov_b32_e32 v45, v37
	v_lshlrev_b32_e32 v42, 2, v4
	v_mov_b32_e32 v43, v37
	v_lshlrev_b32_e32 v40, 2, v6
	v_mov_b32_e32 v41, v37
	s_movk_i32 s25, 0xf000
	s_mov_b32 s24, 0x3a800000
	s_mov_b32 s38, 0x358637bd
	s_mov_b32 s39, 0x800000
	s_mov_b64 s[42:43], 0x2000
	s_mov_b64 s[44:45], 0x4000
	s_movk_i32 s46, 0x7ff
	v_mov_b32_e32 v33, v32
